# attention loop VALU trims: row-sum chains start with a 2-operand add, cross-half row-sum combine deferred to loop exit, canonicalising v_max x,x,x dropped in max reductions
# speedup vs baseline: 1.0100x; 1.0100x over previous
; __device__ __forceinline__ void finishSM(f32x16& p0, f32x16& p1, float alpha, float& l_reg, bf16x8& pa0, bf16x8& pa1, bf16x8& pa2, bf16x8& pa3) {
; #pragma unroll
;     for (int r = 0; r < 16; ++r) p1[r] = __builtin_amdgcn_exp2f(p1[r]);
;     float ps = 0;
; #pragma unroll
;     for (int r = 0; r < 16; ++r) ps += p0[r];
; #pragma unroll
;     for (int r = 0; r < 16; ++r) ps += p1[r];
;     { auto rr = __builtin_amdgcn_permlane32_swap(__float_as_uint(ps), __float_as_uint(ps), false, false);
;       ps = __uint_as_float(rr[0]) + __uint_as_float(rr[1]); }
;     l_reg = l_reg * alpha + ps;
;     ...
;     PK4(p0, 0, pa0); PK4(p0, 8, pa1); PK4(p1, 0, pa2); PK4(p1, 8, pa3);
;     ...
; }
; template <int KB>
; __device__ __forceinline__ void qkt(f32x16& p0, f32x16& p1, const char* K_lds, int r32, int hi, const bf16x8* qr) {
;     p0 = f32x16{}; p1 = f32x16{};
;     const char* kb[4];
; #pragma unroll
;     for (int dd = 0; dd < 4; ++dd) kb[dd] = K_lds + KB * SHM_K + KSWZ(r32, (dd * 16 + hi * 8) * 2);
; #pragma unroll
;     for (int d0 = 0; d0 < 8; ++d0) { const char* a = kb[d0 & 3] + (d0 >> 2) * 128;
;         bf16x8 b0 = *reinterpret_cast<const bf16x8*>(a);
;         bf16x8 b1 = *reinterpret_cast<const bf16x8*>(a + 32 * 256);
;         p0 = __builtin_amdgcn_mfma_f32_32x32x16_bf16(b0, qr[d0], p0, 0, 0, 0);
;         p1 = __builtin_amdgcn_mfma_f32_32x32x16_bf16(b1, qr[d0], p1, 0, 0, 0); }
; }
.LBB0_1299:
	v_add_u32_e32 v146, -8, v179
	global_load_dwordx2 v[146:147], v146, s[68:69]
	v_lshl_add_u64 v[130:131], v[188:189], 0, v[170:171]
	v_lshl_add_u64 v[138:139], v[190:191], 0, v[170:171]
	v_lshl_add_u64 v[134:135], v[130:131], 0, s[100:101]
	v_lshl_add_u64 v[130:131], v[130:131], 0, s[16:17]
	v_lshl_add_u64 v[142:143], v[138:139], 0, s[100:101]
	v_lshl_add_u64 v[138:139], v[138:139], 0, s[16:17]
	global_load_dwordx4 v[130:133], v[130:131], off
	global_load_dwordx4 v[134:137], v[134:135], off
	global_load_dwordx4 v[138:141], v[138:139], off
	global_load_dwordx4 v[142:145], v[142:143], off
	ds_read_b128 v[66:69], v199 offset:49152
	ds_read_b128 v[82:85], v199 offset:57344
	ds_read_b128 v[172:175], v200 offset:49152
	ds_read_b128 v[232:235], v200 offset:57344
	ds_read_b128 v[236:239], v201 offset:49152
	ds_read_b128 v[240:243], v201 offset:57344
	ds_read_b128 v[244:247], v202 offset:49152
	v_exp_f32_e32 v209, v150
	v_add_f32_e32 v150, v220, v219
	v_add_f32_e32 v150, v221, v150
	s_waitcnt lgkmcnt(6)
	v_mfma_f32_32x32x16_bf16 v[66:81], v[66:69], v[126:129], 0
	v_add_f32_e32 v150, v222, v150
	v_add_f32_e32 v150, v223, v150
	v_add_f32_e32 v150, v225, v150
	v_add_f32_e32 v150, v224, v150
	v_add_f32_e32 v150, v226, v150
	s_waitcnt lgkmcnt(5)
	v_mfma_f32_32x32x16_bf16 v[82:97], v[82:85], v[126:129], 0
	v_add_f32_e32 v150, v211, v150
	v_add_f32_e32 v150, v212, v150
	v_exp_f32_e32 v194, v194
	s_waitcnt lgkmcnt(4)
	v_mfma_f32_32x32x16_bf16 v[66:81], v[172:175], v[122:125], v[66:81]
	ds_read_b128 v[172:175], v202 offset:57344
	v_exp_f32_e32 v195, v195
	v_exp_f32_e32 v192, v192
	v_exp_f32_e32 v193, v193
	s_waitcnt lgkmcnt(4)
	v_mfma_f32_32x32x16_bf16 v[82:97], v[232:235], v[122:125], v[82:97]
	ds_read_b128 v[232:235], v199 offset:49280
	v_exp_f32_e32 v158, v158
	v_exp_f32_e32 v159, v159
	s_waitcnt lgkmcnt(4)
	v_mfma_f32_32x32x16_bf16 v[66:81], v[236:239], v[118:121], v[66:81]
	ds_read_b128 v[236:239], v199 offset:57472
	v_exp_f32_e32 v207, v154
	v_exp_f32_e32 v208, v155
	v_exp_f32_e32 v210, v151
	s_waitcnt lgkmcnt(4)
	v_mfma_f32_32x32x16_bf16 v[82:97], v[240:243], v[118:121], v[82:97]
	ds_read_b128 v[240:243], v200 offset:49280
	v_exp_f32_e32 v160, v160
	v_exp_f32_e32 v161, v161
	s_waitcnt lgkmcnt(4)
	v_mfma_f32_32x32x16_bf16 v[66:81], v[244:247], v[114:117], v[66:81]
	ds_read_b128 v[244:247], v200 offset:57472
	v_exp_f32_e32 v227, v156
	v_cvt_pk_bf16_f32 v151, v224, v226
	v_cvt_pk_bf16_f32 v154, v214, v216
	v_cvt_pk_bf16_f32 v155, v217, v218
	v_cvt_pk_bf16_f32 v156, v194, v195
	s_waitcnt lgkmcnt(4)
	v_mfma_f32_32x32x16_bf16 v[82:97], v[172:175], v[114:117], v[82:97]
	ds_read_b128 v[172:175], v201 offset:49280
	v_exp_f32_e32 v228, v157
	v_exp_f32_e32 v229, v152
	s_waitcnt lgkmcnt(4)
	v_mfma_f32_32x32x16_bf16 v[66:81], v[232:235], v[110:113], v[66:81]
	ds_read_b128 v[232:235], v201 offset:57472
	v_exp_f32_e32 v230, v153
	v_cvt_pk_bf16_f32 v152, v211, v212
	v_cvt_pk_bf16_f32 v153, v213, v215
	v_cvt_pk_bf16_f32 v157, v192, v193
	v_cvt_pk_bf16_f32 v211, v229, v230
	s_waitcnt lgkmcnt(4)
	v_mfma_f32_32x32x16_bf16 v[82:97], v[236:239], v[110:113], v[82:97]
	ds_read_b128 v[236:239], v202 offset:49280
	v_permlane32_swap_b32_e32 v152, v154
	v_permlane32_swap_b32_e32 v153, v155
	v_add_f32_e32 v249, v213, v150
	v_add_f32_e32 v249, v215, v249
	v_add_f32_e32 v249, v214, v249
	s_waitcnt lgkmcnt(4)
	v_mfma_f32_32x32x16_bf16 v[66:81], v[240:243], v[106:109], v[66:81]
	ds_read_b128 v[240:243], v202 offset:57472
	v_add_f32_e32 v249, v216, v249
	v_add_f32_e32 v249, v217, v249
	v_add_f32_e32 v249, v218, v249
	v_add_f32_e32 v249, v194, v249
	v_add_f32_e32 v248, v195, v249
	s_waitcnt lgkmcnt(4)
	v_mfma_f32_32x32x16_bf16 v[82:97], v[244:247], v[106:109], v[82:97]
	v_add_f32_e32 v248, v192, v248
	v_add_f32_e32 v248, v193, v248
	v_add_f32_e32 v248, v158, v248
	v_add_f32_e32 v248, v159, v248
	v_add_f32_e32 v248, v207, v248
	s_waitcnt lgkmcnt(3)
	v_mfma_f32_32x32x16_bf16 v[66:81], v[172:175], v[102:105], v[66:81]
	v_add_f32_e32 v248, v208, v248
	v_add_f32_e32 v248, v209, v248
	v_add_f32_e32 v248, v210, v248
	v_add_f32_e32 v248, v160, v248
	v_add_f32_e32 v248, v161, v248
	s_waitcnt lgkmcnt(2)
	v_mfma_f32_32x32x16_bf16 v[82:97], v[232:235], v[102:105], v[82:97]
	v_add_f32_e32 v248, v227, v248
	v_add_f32_e32 v248, v228, v248
	v_add_f32_e32 v248, v229, v248
	v_add_f32_e32 v181, v230, v248
	s_waitcnt lgkmcnt(1)
	v_mfma_f32_32x32x16_bf16 v[66:81], v[236:239], v[98:101], v[66:81]
	v_cvt_pk_bf16_f32 v148, v219, v220
	v_cvt_pk_bf16_f32 v149, v221, v222
	v_cvt_pk_bf16_f32 v150, v223, v225
	v_cvt_pk_bf16_f32 v158, v158, v159
	v_cvt_pk_bf16_f32 v159, v207, v208
	s_waitcnt lgkmcnt(0)
	v_mfma_f32_32x32x16_bf16 v[82:97], v[240:243], v[98:101], v[82:97]
	v_cvt_pk_bf16_f32 v208, v209, v210
	v_cvt_pk_bf16_f32 v210, v227, v228
	v_permlane32_swap_b32_e32 v148, v150
	v_permlane32_swap_b32_e32 v149, v151
	v_cvt_pk_bf16_f32 v209, v160, v161
	v_permlane32_swap_b32_e32 v208, v210
	v_permlane32_swap_b32_e32 v156, v158
	v_permlane32_swap_b32_e32 v157, v159
	v_permlane32_swap_b32_e32 v209, v211
	v_lshl_add_u64 v[194:195], v[188:189], 0, v[170:171]
	v_lshl_add_u64 v[192:193], v[190:191], 0, v[170:171]
	ds_read_b64_tr_b16 v[172:173], v1 offset:0x0
	ds_read_b64_tr_b16 v[174:175], v1 offset:0x800
	ds_read_b64_tr_b16 v[212:213], v1 offset:0x200
	ds_read_b64_tr_b16 v[214:215], v1 offset:0xa00
	ds_read_b64_tr_b16 v[216:217], v1 offset:0x400
	ds_read_b64_tr_b16 v[218:219], v1 offset:0xc00
	ds_read_b64_tr_b16 v[220:221], v1 offset:0x600
	ds_read_b64_tr_b16 v[222:223], v1 offset:0xe00
	ds_read_b64_tr_b16 v[224:225], v1 offset:0x1000
	ds_read_b64_tr_b16 v[226:227], v1 offset:0x1800
	ds_read_b64_tr_b16 v[232:233], v1 offset:0x1200
	ds_read_b64_tr_b16 v[234:235], v1 offset:0x1a00
	ds_read_b64_tr_b16 v[236:237], v1 offset:0x1400
	ds_read_b64_tr_b16 v[238:239], v1 offset:0x1c00
	s_nop 0
	s_waitcnt lgkmcnt(12)
; __device__ __forceinline__ void sel_mask_tile(f32x16& p0, f32x16& p1, unsigned wlo, unsigned whi, int hi) {
;     const unsigned NEGB = 0xff800000u;
;     const unsigned lo = wlo >> (4 * hi), h2 = whi >> (4 * hi);
; #pragma unroll
;     for (int r = 0; r < 16; ++r) {
;         const int c = (r & 3) + 8 * (r >> 2);
;         const unsigned m0 = (unsigned)__builtin_amdgcn_sbfe((int)lo, c, 1), m1 = (unsigned)__builtin_amdgcn_sbfe((int)h2, c, 1);
;         p0[r] = __uint_as_float((__float_as_uint(p0[r]) & m0) | (NEGB & ~m0));
;         p1[r] = __uint_as_float((__float_as_uint(p1[r]) & m1) | (NEGB & ~m1));
;     }
; }
; __device__ __forceinline__ void partialSM(f32x16& p0, f32x16& p1, float& m_reg, float& mn, float& alpha) {
;     float pmax = p0[0];
; #pragma unroll
;     for (int r = 1; r < 16; ++r) pmax = fmaxf(pmax, p0[r]);
; #pragma unroll
;     for (int r = 0; r < 16; ++r) pmax = fmaxf(pmax, p1[r]);
;     { auto rr = __builtin_amdgcn_permlane32_swap(__float_as_uint(pmax), __float_as_uint(pmax), false, false);
;       pmax = fmaxf(__uint_as_float(rr[0]), __uint_as_float(rr[1])); }
;     constexpr float C2 = 1.4426950408889634f * SCALE;
;     if (__builtin_expect(__all((pmax - m_reg) * SCALE <= THR), 1)) { mn = m_reg; alpha = 1.f; }
; template <int VB>
; __device__ __forceinline__ void pv_tile(f32x16* o, int vb0, bf16x8 pa0, bf16x8 pa1, bf16x8 pa2, bf16x8 pa3) {
;     ...
;     PV_D0(0); PV_D0(1); PV_D0(2); PV_D0(3);
	v_mfma_f32_32x32x16_bf16 v[2:17], v[148:151], v[172:175], v[2:17]
	ds_read_b64_tr_b16 v[240:241], v1 offset:0x1600
	ds_read_b64_tr_b16 v[242:243], v1 offset:0x1e00
	s_waitcnt vmcnt(4)
	v_lshrrev_b32_e32 v160, v163, v146
	v_lshrrev_b32_e32 v161, v163, v147
	v_bfe_i32 v146, v160, 0, 1
	v_bfe_i32 v147, v161, 0, 1
	v_bitop3_b32 v146, v66, s74, v146 bitop3:0xe4
	v_bitop3_b32 v66, v82, s74, v147 bitop3:0xe4
	s_waitcnt lgkmcnt(12)
	v_mfma_f32_32x32x16_bf16 v[50:65], v[148:151], v[212:215], v[50:65]
	ds_read_b64_tr_b16 v[244:245], v1 offset:0x2000
	ds_read_b64_tr_b16 v[246:247], v1 offset:0x2800
	v_bfe_i32 v82, v160, 1, 1
	v_bfe_i32 v147, v161, 1, 1
	v_bitop3_b32 v82, v67, s74, v82 bitop3:0xe4
	v_bitop3_b32 v67, v83, s74, v147 bitop3:0xe4
	v_bfe_i32 v83, v160, 2, 1
	v_bfe_i32 v147, v161, 2, 1
	s_waitcnt lgkmcnt(12)
	v_mfma_f32_32x32x16_bf16 v[34:49], v[148:151], v[216:219], v[34:49]
	ds_read_b64_tr_b16 v[248:249], v1 offset:0x2200
	ds_read_b64_tr_b16 v[250:251], v1 offset:0x2a00
	v_bitop3_b32 v83, v68, s74, v83 bitop3:0xe4
	v_bitop3_b32 v68, v84, s74, v147 bitop3:0xe4
	v_bfe_i32 v84, v160, 3, 1
	s_waitcnt lgkmcnt(12)
	v_mfma_f32_32x32x16_bf16 v[18:33], v[148:151], v[220:223], v[18:33]
	ds_read_b64_tr_b16 v[220:221], v1 offset:0x2400
	ds_read_b64_tr_b16 v[222:223], v1 offset:0x2c00
	v_bfe_i32 v148, v161, 3, 1
	v_bitop3_b32 v147, v69, s74, v84 bitop3:0xe4
	v_bfe_i32 v84, v160, 8, 1
	v_bitop3_b32 v69, v85, s74, v148 bitop3:0xe4
	v_bfe_i32 v85, v161, 8, 1
	v_bitop3_b32 v148, v70, s74, v84 bitop3:0xe4
	v_bfe_i32 v84, v160, 9, 1
	s_waitcnt lgkmcnt(12)
	v_mfma_f32_32x32x16_bf16 v[2:17], v[152:155], v[224:227], v[2:17]
	ds_read_b64_tr_b16 v[224:225], v1 offset:0x2600
	ds_read_b64_tr_b16 v[226:227], v1 offset:0x2e00
	v_bitop3_b32 v70, v86, s74, v85 bitop3:0xe4
	v_bfe_i32 v85, v161, 9, 1
	v_bitop3_b32 v149, v71, s74, v84 bitop3:0xe4
	v_bfe_i32 v84, v160, 10, 1
	v_bitop3_b32 v71, v87, s74, v85 bitop3:0xe4
	v_bfe_i32 v85, v161, 10, 1
	s_waitcnt lgkmcnt(12)
	v_mfma_f32_32x32x16_bf16 v[50:65], v[152:155], v[232:235], v[50:65]
	ds_read_b64_tr_b16 v[232:233], v1 offset:0x3000
	ds_read_b64_tr_b16 v[234:235], v1 offset:0x3800
	v_bitop3_b32 v87, v72, s74, v84 bitop3:0xe4
	v_bfe_i32 v84, v160, 11, 1
	v_bitop3_b32 v72, v88, s74, v85 bitop3:0xe4
	v_bfe_i32 v85, v161, 11, 1
	v_bitop3_b32 v88, v73, s74, v84 bitop3:0xe4
	v_bfe_i32 v73, v160, 16, 1
	v_bitop3_b32 v84, v89, s74, v85 bitop3:0xe4
	s_waitcnt lgkmcnt(12)
	v_mfma_f32_32x32x16_bf16 v[34:49], v[152:155], v[236:239], v[34:49]
	ds_read_b64_tr_b16 v[236:237], v1 offset:0x3200
	ds_read_b64_tr_b16 v[238:239], v1 offset:0x3a00
	v_bfe_i32 v85, v161, 16, 1
	v_bitop3_b32 v89, v74, s74, v73 bitop3:0xe4
	v_bfe_i32 v73, v160, 17, 1
	v_bfe_i32 v74, v161, 17, 1
	v_bitop3_b32 v85, v90, s74, v85 bitop3:0xe4
	v_bitop3_b32 v90, v75, s74, v73 bitop3:0xe4
	s_waitcnt lgkmcnt(12)
	v_mfma_f32_32x32x16_bf16 v[18:33], v[152:155], v[240:243], v[18:33]
	ds_read_b64_tr_b16 v[240:241], v1 offset:0x3400
	ds_read_b64_tr_b16 v[242:243], v1 offset:0x3c00
	v_bitop3_b32 v86, v91, s74, v74 bitop3:0xe4
	v_bfe_i32 v73, v160, 18, 1
	v_bfe_i32 v74, v161, 18, 1
	v_bitop3_b32 v91, v76, s74, v73 bitop3:0xe4
	v_bitop3_b32 v76, v92, s74, v74 bitop3:0xe4
	v_bfe_i32 v73, v160, 19, 1
	v_bfe_i32 v74, v161, 19, 1
	s_waitcnt lgkmcnt(12)
	v_mfma_f32_32x32x16_bf16 v[2:17], v[156:159], v[244:247], v[2:17]
	ds_read_b64_tr_b16 v[244:245], v1 offset:0x3600
	ds_read_b64_tr_b16 v[246:247], v1 offset:0x3e00
	v_bitop3_b32 v92, v77, s74, v73 bitop3:0xe4
	v_bitop3_b32 v77, v93, s74, v74 bitop3:0xe4
	v_bfe_i32 v73, v160, 24, 1
	v_bfe_i32 v74, v161, 24, 1
	v_bitop3_b32 v93, v78, s74, v73 bitop3:0xe4
	v_bitop3_b32 v78, v94, s74, v74 bitop3:0xe4
	s_waitcnt lgkmcnt(12)
	v_mfma_f32_32x32x16_bf16 v[50:65], v[156:159], v[248:251], v[50:65]
	v_bfe_i32 v73, v160, 25, 1
	v_bfe_i32 v74, v161, 25, 1
	v_bitop3_b32 v79, v79, s74, v73 bitop3:0xe4
	v_bitop3_b32 v73, v95, s74, v74 bitop3:0xe4
	v_bfe_i32 v74, v160, 26, 1
	v_bfe_i32 v75, v161, 26, 1
	v_bitop3_b32 v80, v80, s74, v74 bitop3:0xe4
	s_waitcnt lgkmcnt(10)
	v_mfma_f32_32x32x16_bf16 v[34:49], v[156:159], v[220:223], v[34:49]
	v_bitop3_b32 v74, v96, s74, v75 bitop3:0xe4
	v_bfe_i32 v75, v160, 27, 1
	v_bfe_i32 v94, v161, 27, 1
	v_bitop3_b32 v81, v81, s74, v75 bitop3:0xe4
	v_bitop3_b32 v75, v97, s74, v94 bitop3:0xe4
	s_waitcnt lgkmcnt(8)
	v_mfma_f32_32x32x16_bf16 v[18:33], v[156:159], v[224:227], v[18:33]
	v_max_f32_e32 v94, v146, v82
	v_max3_f32 v94, v94, v83, v147
	v_max3_f32 v94, v94, v148, v149
	v_max3_f32 v94, v94, v87, v88
	v_max3_f32 v94, v94, v89, v90
	v_max3_f32 v94, v94, v91, v92
	s_waitcnt lgkmcnt(6)
	v_mfma_f32_32x32x16_bf16 v[2:17], v[208:211], v[232:235], v[2:17]
	v_max3_f32 v94, v94, v93, v79
	v_max3_f32 v94, v94, v80, v81
	v_max3_f32 v94, v94, v66, v67
	v_max3_f32 v94, v94, v68, v69
	v_max3_f32 v94, v94, v70, v71
	v_max3_f32 v94, v94, v72, v84
	s_waitcnt lgkmcnt(4)
	v_mfma_f32_32x32x16_bf16 v[50:65], v[208:211], v[236:239], v[50:65]
	v_max3_f32 v94, v94, v85, v86
	v_max3_f32 v94, v94, v76, v77
	v_max3_f32 v94, v94, v78, v73
	v_max3_f32 v94, v94, v74, v75
	v_mov_b32_e32 v95, v94
	s_nop 1
	v_permlane32_swap_b32_e32 v94, v95
	s_waitcnt lgkmcnt(2)
	v_mfma_f32_32x32x16_bf16 v[34:49], v[208:211], v[240:243], v[34:49]
	v_max_f32_e32 v94, v94, v95
	v_sub_f32_e32 v95, v94, v206
	v_max_f32_e32 v94, v206, v94
	v_sub_f32_e32 v96, v206, v94
	s_waitcnt lgkmcnt(0)
	v_mfma_f32_32x32x16_bf16 v[18:33], v[208:211], v[244:247], v[18:33]
	s_waitcnt vmcnt(0)
	ds_write_b128 v204, v[138:141] offset:32768
	ds_write_b128 v204, v[142:145] offset:40960
	v_mul_f32_e32 v96, 0x3e0293ee, v96
	v_mul_f32_e32 v95, 0x3db504f3, v95
	v_exp_f32_e32 v96, v96
	v_cmp_ge_f32_e32 vcc, s75, v95
	s_cmp_eq_u64 vcc, exec
	s_cselect_b64 s[6:7], -1, 0
	s_barrier
	s_waitcnt vmcnt(0)
	v_cndmask_b32_e64 v208, v96, 1.0, s[6:7]
	v_cmp_gt_f32_e32 vcc, 1.0, v208
	ds_write_b128 v197, v[130:133]
	ds_write_b128 v198, v[134:137]
	s_cbranch_vccz .LBB0_1303
	s_and_saveexec_b64 s[36:37], s[0:1]
	ds_write_b32 v185, v208 offset:128
	s_or_b64 exec, exec, s[36:37]
	s_waitcnt lgkmcnt(0)
	ds_read_b128 v[150:153], v183 offset:224
	ds_read_b128 v[154:157], v183 offset:192
	ds_read_b128 v[158:161], v183 offset:160
	ds_read_b128 v[172:175], v183 offset:128
	s_waitcnt lgkmcnt(3)
	v_pk_mul_f32 v[16:17], v[16:17], v[152:153]
	s_waitcnt lgkmcnt(2)
	v_pk_mul_f32 v[12:13], v[12:13], v[156:157]
	s_waitcnt lgkmcnt(1)
	v_pk_mul_f32 v[8:9], v[8:9], v[160:161]
	s_waitcnt lgkmcnt(0)
	v_pk_mul_f32 v[4:5], v[4:5], v[174:175]
	v_pk_mul_f32 v[14:15], v[14:15], v[150:151]
	v_pk_mul_f32 v[10:11], v[10:11], v[154:155]
	v_pk_mul_f32 v[6:7], v[6:7], v[158:159]
	v_pk_mul_f32 v[2:3], v[2:3], v[172:173]
	v_pk_mul_f32 v[64:65], v[64:65], v[152:153]
	v_pk_mul_f32 v[60:61], v[60:61], v[156:157]
	v_pk_mul_f32 v[56:57], v[56:57], v[160:161]
	v_pk_mul_f32 v[52:53], v[52:53], v[174:175]
	v_pk_mul_f32 v[62:63], v[62:63], v[150:151]
	v_pk_mul_f32 v[58:59], v[58:59], v[154:155]
	v_pk_mul_f32 v[54:55], v[54:55], v[158:159]
	v_pk_mul_f32 v[50:51], v[50:51], v[172:173]
	v_pk_mul_f32 v[48:49], v[48:49], v[152:153]
	v_pk_mul_f32 v[44:45], v[44:45], v[156:157]
	v_pk_mul_f32 v[40:41], v[40:41], v[160:161]
	v_pk_mul_f32 v[36:37], v[36:37], v[174:175]
	v_pk_mul_f32 v[46:47], v[46:47], v[150:151]
	v_pk_mul_f32 v[42:43], v[42:43], v[154:155]
	v_pk_mul_f32 v[38:39], v[38:39], v[158:159]
	v_pk_mul_f32 v[34:35], v[34:35], v[172:173]
	v_pk_mul_f32 v[32:33], v[32:33], v[152:153]
	v_pk_mul_f32 v[28:29], v[28:29], v[156:157]
	v_pk_mul_f32 v[24:25], v[24:25], v[160:161]
	v_pk_mul_f32 v[20:21], v[20:21], v[174:175]
	v_pk_mul_f32 v[30:31], v[30:31], v[150:151]
	v_pk_mul_f32 v[26:27], v[26:27], v[154:155]
	v_pk_mul_f32 v[22:23], v[22:23], v[158:159]
	v_pk_mul_f32 v[18:19], v[18:19], v[172:173]

; __device__ __forceinline__ void finishSM(f32x16& p0, f32x16& p1, float alpha, float& l_reg, bf16x8& pa0, bf16x8& pa1, bf16x8& pa2, bf16x8& pa3) {
; #pragma unroll
;     for (int r = 0; r < 16; ++r) p1[r] = __builtin_amdgcn_exp2f(p1[r]);
;     float ps = 0;
; #pragma unroll
;     for (int r = 0; r < 16; ++r) ps += p0[r];
; #pragma unroll
;     for (int r = 0; r < 16; ++r) ps += p1[r];
;     { auto rr = __builtin_amdgcn_permlane32_swap(__float_as_uint(ps), __float_as_uint(ps), false, false);
;       ps = __uint_as_float(rr[0]) + __uint_as_float(rr[1]); }
;     l_reg = l_reg * alpha + ps;
;     ...
;     PK4(p0, 0, pa0); PK4(p0, 8, pa1); PK4(p1, 0, pa2); PK4(p1, 8, pa3);
; template <int KB>
; __device__ __forceinline__ void qkt(f32x16& p0, f32x16& p1, const char* K_lds, int r32, int hi, const bf16x8* qr) {
;     p0 = f32x16{}; p1 = f32x16{};
;     const char* kb[4];
; #pragma unroll
;     for (int dd = 0; dd < 4; ++dd) kb[dd] = K_lds + KB * SHM_K + KSWZ(r32, (dd * 16 + hi * 8) * 2);
; #pragma unroll
;     for (int d0 = 0; d0 < 8; ++d0) { const char* a = kb[d0 & 3] + (d0 >> 2) * 128;
;         bf16x8 b0 = *reinterpret_cast<const bf16x8*>(a);
;         bf16x8 b1 = *reinterpret_cast<const bf16x8*>(a + 32 * 256);
;         p0 = __builtin_amdgcn_mfma_f32_32x32x16_bf16(b0, qr[d0], p0, 0, 0, 0);
;         p1 = __builtin_amdgcn_mfma_f32_32x32x16_bf16(b1, qr[d0], p1, 0, 0, 0); }
; }
.Lp5_a2:
	ds_read_b128 v[66:69], v199 offset:32768
	ds_read_b128 v[70:73], v199 offset:40960
	ds_read_b128 v[172:175], v200 offset:32768
	ds_read_b128 v[224:227], v200 offset:40960
	ds_read_b128 v[232:235], v201 offset:32768
	ds_read_b128 v[236:239], v201 offset:40960
	ds_read_b128 v[240:243], v202 offset:32768
	ds_read_b128 v[244:247], v202 offset:40960
	v_exp_f32_e32 v211, v211
	v_exp_f32_e32 v212, v212
	s_waitcnt lgkmcnt(7)
	v_mfma_f32_32x32x16_bf16 v[82:97], v[66:69], v[126:129], 0
	v_exp_f32_e32 v213, v213
	v_exp_f32_e32 v214, v214
	v_exp_f32_e32 v215, v215
	s_waitcnt lgkmcnt(6)
	v_mfma_f32_32x32x16_bf16 v[66:81], v[70:73], v[126:129], 0
	v_exp_f32_e32 v216, v216
	v_exp_f32_e32 v207, v207
	s_waitcnt lgkmcnt(5)
	v_mfma_f32_32x32x16_bf16 v[82:97], v[172:175], v[122:125], v[82:97]
	ds_read_b128 v[172:175], v199 offset:32896
	v_exp_f32_e32 v250, v219
	v_exp_f32_e32 v219, v209
	v_add_f32_e32 v209, v147, v146
	s_waitcnt lgkmcnt(5)
	v_mfma_f32_32x32x16_bf16 v[66:81], v[224:227], v[122:125], v[66:81]
	ds_read_b128 v[224:227], v199 offset:41088
	v_add_f32_e32 v209, v148, v209
	v_add_f32_e32 v209, v159, v209
	v_add_f32_e32 v209, v160, v209
	v_add_f32_e32 v209, v161, v209
	v_add_f32_e32 v209, v149, v209
	s_waitcnt lgkmcnt(5)
	v_mfma_f32_32x32x16_bf16 v[82:97], v[232:235], v[118:121], v[82:97]
	ds_read_b128 v[232:235], v200 offset:32896
	v_add_f32_e32 v209, v158, v209
	v_add_f32_e32 v209, v150, v209
	v_add_f32_e32 v209, v151, v209
	v_add_f32_e32 v209, v155, v209
	v_add_f32_e32 v209, v157, v209
	s_waitcnt lgkmcnt(5)
	v_mfma_f32_32x32x16_bf16 v[66:81], v[236:239], v[118:121], v[66:81]
	ds_read_b128 v[236:239], v200 offset:41088
	v_exp_f32_e32 v248, v217
	v_add_f32_e32 v209, v152, v209
	v_exp_f32_e32 v249, v218
	s_waitcnt lgkmcnt(5)
	v_mfma_f32_32x32x16_bf16 v[82:97], v[240:243], v[114:117], v[82:97]
	ds_read_b128 v[240:243], v201 offset:32896
	v_add_f32_e32 v209, v153, v209
	v_add_f32_e32 v209, v154, v209
	v_exp_f32_e32 v251, v220
	v_add_f32_e32 v209, v156, v209
	s_waitcnt lgkmcnt(5)
	v_mfma_f32_32x32x16_bf16 v[66:81], v[244:247], v[114:117], v[66:81]
	ds_read_b128 v[244:247], v201 offset:41088
	v_exp_f32_e32 v217, v221
	v_add_f32_e32 v209, v248, v209
	v_exp_f32_e32 v218, v210
	s_waitcnt lgkmcnt(5)
	v_mfma_f32_32x32x16_bf16 v[82:97], v[172:175], v[110:113], v[82:97]
	ds_read_b128 v[172:175], v202 offset:32896
	v_add_f32_e32 v209, v249, v209
	v_add_f32_e32 v209, v250, v209
	v_add_f32_e32 v209, v251, v209
	v_add_f32_e32 v209, v217, v209
	v_add_f32_e32 v209, v218, v209
	s_waitcnt lgkmcnt(5)
	v_mfma_f32_32x32x16_bf16 v[66:81], v[224:227], v[110:113], v[66:81]
	ds_read_b128 v[224:227], v202 offset:41088
	v_add_f32_e32 v209, v211, v209
	v_add_f32_e32 v209, v212, v209
	v_add_f32_e32 v209, v213, v209
	v_exp_f32_e32 v220, v222
	s_waitcnt lgkmcnt(5)
	v_mfma_f32_32x32x16_bf16 v[82:97], v[232:235], v[106:109], v[82:97]
	v_add_f32_e32 v209, v214, v209
	v_exp_f32_e32 v221, v223
	v_add_f32_e32 v209, v215, v209
	v_add_f32_e32 v209, v216, v209
	s_waitcnt lgkmcnt(4)
	v_mfma_f32_32x32x16_bf16 v[66:81], v[236:239], v[106:109], v[66:81]
	v_add_f32_e32 v209, v219, v209
	v_add_f32_e32 v209, v220, v209
	v_add_f32_e32 v209, v221, v209
	v_add_f32_e32 v209, v207, v209
	s_waitcnt lgkmcnt(3)
	v_mfma_f32_32x32x16_bf16 v[82:97], v[240:243], v[102:105], v[82:97]
	v_cvt_pk_bf16_f32 v146, v146, v147
	v_cvt_pk_bf16_f32 v147, v148, v159
	v_cvt_pk_bf16_f32 v148, v160, v161
	v_cvt_pk_bf16_f32 v149, v149, v158
	v_cvt_pk_bf16_f32 v150, v150, v151
	s_waitcnt lgkmcnt(2)
	v_mfma_f32_32x32x16_bf16 v[66:81], v[244:247], v[102:105], v[66:81]
	v_cvt_pk_bf16_f32 v151, v155, v157
	v_cvt_pk_bf16_f32 v152, v152, v153
	v_cvt_pk_bf16_f32 v153, v154, v156
	v_cvt_pk_bf16_f32 v154, v248, v249
	v_cvt_pk_bf16_f32 v155, v250, v251
	s_waitcnt lgkmcnt(1)
	v_mfma_f32_32x32x16_bf16 v[82:97], v[172:175], v[98:101], v[82:97]
	v_cvt_pk_bf16_f32 v156, v217, v218
	v_cvt_pk_bf16_f32 v157, v211, v212
	v_cvt_pk_bf16_f32 v158, v213, v214
	v_cvt_pk_bf16_f32 v159, v215, v216
	v_cvt_pk_bf16_f32 v160, v219, v220
	s_waitcnt lgkmcnt(0)
	v_mfma_f32_32x32x16_bf16 v[66:81], v[224:227], v[98:101], v[66:81]
	v_cvt_pk_bf16_f32 v161, v221, v207
	v_permlane32_swap_b32_e32 v146, v148
	v_permlane32_swap_b32_e32 v147, v149
	v_permlane32_swap_b32_e32 v150, v152
	v_permlane32_swap_b32_e32 v151, v153
	v_permlane32_swap_b32_e32 v154, v156
	v_permlane32_swap_b32_e32 v155, v157
	v_permlane32_swap_b32_e32 v158, v160
	v_permlane32_swap_b32_e32 v159, v161
	s_add_i32 s82, s82, 2
	s_cmp_le_u32 s82, s81
	s_cselect_b64 s[36:37], -1, 0
	s_cmp_gt_u32 s82, s81
	s_cbranch_scc1 .Lp5_skip_ld
; __device__ __forceinline__ void sel_mask_tile(f32x16& p0, f32x16& p1, unsigned wlo, unsigned whi, int hi) {
;     const unsigned NEGB = 0xff800000u;
;     const unsigned lo = wlo >> (4 * hi), h2 = whi >> (4 * hi);
; #pragma unroll
;     for (int r = 0; r < 16; ++r) {
;         const int c = (r & 3) + 8 * (r >> 2);
;         const unsigned m0 = (unsigned)__builtin_amdgcn_sbfe((int)lo, c, 1), m1 = (unsigned)__builtin_amdgcn_sbfe((int)h2, c, 1);
;         p0[r] = __uint_as_float((__float_as_uint(p0[r]) & m0) | (NEGB & ~m0));
;         p1[r] = __uint_as_float((__float_as_uint(p1[r]) & m1) | (NEGB & ~m1));
;     }
; }
; __device__ __forceinline__ void partialSM(f32x16& p0, f32x16& p1, float& m_reg, float& mn, float& alpha) {
;     float pmax = p0[0];
; #pragma unroll
;     for (int r = 1; r < 16; ++r) pmax = fmaxf(pmax, p0[r]);
; #pragma unroll
;     for (int r = 0; r < 16; ++r) pmax = fmaxf(pmax, p1[r]);
;     { auto rr = __builtin_amdgcn_permlane32_swap(__float_as_uint(pmax), __float_as_uint(pmax), false, false);
;       pmax = fmaxf(__uint_as_float(rr[0]), __uint_as_float(rr[1])); }
;     constexpr float C2 = 1.4426950408889634f * SCALE;
;     if (__builtin_expect(__all((pmax - m_reg) * SCALE <= THR), 1)) { mn = m_reg; alpha = 1.f; }
; template <int VB>
; __device__ __forceinline__ void pv_tile(f32x16* o, int vb0, bf16x8 pa0, bf16x8 pa1, bf16x8 pa2, bf16x8 pa3) {
;     ...
;     PV_D0(0); PV_D0(1); PV_D0(2); PV_D0(3);
.LBB0_1305:
	ds_read_b64_tr_b16 v[212:213], v1 offset:0x4000
	ds_read_b64_tr_b16 v[214:215], v1 offset:0x4800
	ds_read_b64_tr_b16 v[216:217], v1 offset:0x4200
	ds_read_b64_tr_b16 v[218:219], v1 offset:0x4a00
	ds_read_b64_tr_b16 v[220:221], v1 offset:0x4400
	ds_read_b64_tr_b16 v[222:223], v1 offset:0x4c00
	ds_read_b64_tr_b16 v[224:225], v1 offset:0x4600
	ds_read_b64_tr_b16 v[226:227], v1 offset:0x4e00
	ds_read_b64_tr_b16 v[232:233], v1 offset:0x5000
	ds_read_b64_tr_b16 v[234:235], v1 offset:0x5800
	ds_read_b64_tr_b16 v[236:237], v1 offset:0x5200
	ds_read_b64_tr_b16 v[238:239], v1 offset:0x5a00
	ds_read_b64_tr_b16 v[240:241], v1 offset:0x5400
	ds_read_b64_tr_b16 v[242:243], v1 offset:0x5c00
	s_nop 0
	s_waitcnt lgkmcnt(12)
	v_mfma_f32_32x32x16_bf16 v[2:17], v[146:149], v[212:215], v[2:17]
	ds_read_b64_tr_b16 v[244:245], v1 offset:0x5600
	ds_read_b64_tr_b16 v[246:247], v1 offset:0x5e00
	s_waitcnt vmcnt(4)
	v_lshrrev_b32_e32 v193, v163, v228
	v_bfe_i32 v192, v193, 0, 1
	v_bitop3_b32 v192, v82, s74, v192 bitop3:0xe4
	v_bfe_i32 v82, v193, 1, 1
	s_waitcnt lgkmcnt(12)
	v_mfma_f32_32x32x16_bf16 v[50:65], v[146:149], v[216:219], v[50:65]
	ds_read_b64_tr_b16 v[248:249], v1 offset:0x6000
	ds_read_b64_tr_b16 v[250:251], v1 offset:0x6800
	s_waitcnt lgkmcnt(12)
	v_mfma_f32_32x32x16_bf16 v[34:49], v[146:149], v[220:223], v[34:49]
	ds_read_b64_tr_b16 v[220:221], v1 offset:0x6200
	ds_read_b64_tr_b16 v[222:223], v1 offset:0x6a00
	s_waitcnt lgkmcnt(12)
	v_mfma_f32_32x32x16_bf16 v[18:33], v[146:149], v[224:227], v[18:33]
	ds_read_b64_tr_b16 v[224:225], v1 offset:0x6400
	ds_read_b64_tr_b16 v[226:227], v1 offset:0x6c00
	v_bitop3_b32 v146, v83, s74, v82 bitop3:0xe4
	v_bfe_i32 v82, v193, 2, 1
	v_bitop3_b32 v147, v84, s74, v82 bitop3:0xe4
	v_bfe_i32 v82, v193, 3, 1
	v_bitop3_b32 v148, v85, s74, v82 bitop3:0xe4
	v_bfe_i32 v82, v193, 8, 1
	v_bitop3_b32 v149, v86, s74, v82 bitop3:0xe4
	s_waitcnt lgkmcnt(12)
	v_mfma_f32_32x32x16_bf16 v[2:17], v[150:153], v[232:235], v[2:17]
	ds_read_b64_tr_b16 v[232:233], v1 offset:0x6600
	ds_read_b64_tr_b16 v[234:235], v1 offset:0x6e00
	v_bfe_i32 v82, v193, 9, 1
	s_waitcnt lgkmcnt(12)
	v_mfma_f32_32x32x16_bf16 v[50:65], v[150:153], v[236:239], v[50:65]
	ds_read_b64_tr_b16 v[236:237], v1 offset:0x7000
	ds_read_b64_tr_b16 v[238:239], v1 offset:0x7800
	s_waitcnt lgkmcnt(12)
	v_mfma_f32_32x32x16_bf16 v[34:49], v[150:153], v[240:243], v[34:49]
	ds_read_b64_tr_b16 v[240:241], v1 offset:0x7200
	ds_read_b64_tr_b16 v[242:243], v1 offset:0x7a00
	s_waitcnt lgkmcnt(12)
	v_mfma_f32_32x32x16_bf16 v[18:33], v[150:153], v[244:247], v[18:33]
	ds_read_b64_tr_b16 v[244:245], v1 offset:0x7400
	ds_read_b64_tr_b16 v[246:247], v1 offset:0x7c00
	v_bitop3_b32 v150, v87, s74, v82 bitop3:0xe4
	v_bfe_i32 v82, v193, 10, 1
	v_bitop3_b32 v88, v88, s74, v82 bitop3:0xe4
	v_bfe_i32 v82, v193, 11, 1
	v_bitop3_b32 v89, v89, s74, v82 bitop3:0xe4
	v_bfe_i32 v82, v193, 16, 1
	v_bitop3_b32 v90, v90, s74, v82 bitop3:0xe4
	v_bfe_i32 v82, v193, 17, 1
	v_bitop3_b32 v91, v91, s74, v82 bitop3:0xe4
	s_waitcnt lgkmcnt(12)
	v_mfma_f32_32x32x16_bf16 v[2:17], v[154:157], v[248:251], v[2:17]
	ds_read_b64_tr_b16 v[248:249], v1 offset:0x7600
	ds_read_b64_tr_b16 v[250:251], v1 offset:0x7e00
	v_bfe_i32 v82, v193, 18, 1
	v_bitop3_b32 v92, v92, s74, v82 bitop3:0xe4
	v_bfe_i32 v82, v193, 19, 1
	v_bitop3_b32 v93, v93, s74, v82 bitop3:0xe4
	v_bfe_i32 v82, v193, 24, 1
	v_bitop3_b32 v94, v94, s74, v82 bitop3:0xe4
	v_bfe_i32 v82, v193, 25, 1
	v_bitop3_b32 v95, v95, s74, v82 bitop3:0xe4
	v_bfe_i32 v82, v193, 26, 1
	s_waitcnt lgkmcnt(12)
	v_mfma_f32_32x32x16_bf16 v[50:65], v[154:157], v[220:223], v[50:65]
	v_bitop3_b32 v96, v96, s74, v82 bitop3:0xe4
	v_bfe_i32 v82, v193, 27, 1
	v_bitop3_b32 v97, v97, s74, v82 bitop3:0xe4
	v_max_f32_e32 v82, v192, v146
	v_max3_f32 v82, v82, v147, v148
	v_max3_f32 v82, v82, v149, v150
	v_max3_f32 v82, v82, v88, v89
	s_waitcnt lgkmcnt(10)
	v_mfma_f32_32x32x16_bf16 v[34:49], v[154:157], v[224:227], v[34:49]
	v_max3_f32 v82, v82, v90, v91
	v_lshrrev_b32_e32 v194, v163, v229
	v_max3_f32 v82, v82, v92, v93
	v_bfe_i32 v195, v194, 0, 1
	v_bfe_i32 v172, v194, 1, 1
	v_max3_f32 v82, v82, v94, v95
	v_bitop3_b32 v66, v66, s74, v195 bitop3:0xe4
	v_bfe_i32 v83, v194, 2, 1
	v_bfe_i32 v84, v194, 3, 1
	s_waitcnt lgkmcnt(8)
	v_mfma_f32_32x32x16_bf16 v[18:33], v[154:157], v[232:235], v[18:33]
	v_max3_f32 v230, v82, v96, v97
	v_bitop3_b32 v67, v67, s74, v172 bitop3:0xe4
	v_bfe_i32 v85, v194, 8, 1
	v_bfe_i32 v86, v194, 9, 1
	v_bitop3_b32 v82, v68, s74, v83 bitop3:0xe4
	v_max3_f32 v68, v230, v66, v67
	v_bitop3_b32 v83, v69, s74, v84 bitop3:0xe4
	v_bfe_i32 v87, v194, 10, 1
	v_bfe_i32 v151, v194, 11, 1
	s_waitcnt lgkmcnt(6)
	v_mfma_f32_32x32x16_bf16 v[2:17], v[158:161], v[236:239], v[2:17]
	v_bitop3_b32 v84, v70, s74, v85 bitop3:0xe4
	v_max3_f32 v68, v68, v82, v83
	v_bitop3_b32 v85, v71, s74, v86 bitop3:0xe4
	v_bfe_i32 v152, v194, 16, 1
	v_bfe_i32 v153, v194, 17, 1
	v_bitop3_b32 v86, v72, s74, v87 bitop3:0xe4
	v_max3_f32 v68, v68, v84, v85
	v_bitop3_b32 v87, v73, s74, v151 bitop3:0xe4
	v_bfe_i32 v154, v194, 18, 1
	s_waitcnt lgkmcnt(4)
	v_mfma_f32_32x32x16_bf16 v[50:65], v[158:161], v[240:243], v[50:65]
	v_bfe_i32 v155, v194, 19, 1
	v_bitop3_b32 v74, v74, s74, v152 bitop3:0xe4
	v_max3_f32 v69, v68, v86, v87
	v_bitop3_b32 v75, v75, s74, v153 bitop3:0xe4
	v_bfe_i32 v156, v194, 24, 1
	v_bfe_i32 v157, v194, 25, 1
	v_bitop3_b32 v68, v76, s74, v154 bitop3:0xe4
	v_max3_f32 v71, v69, v74, v75
	v_bitop3_b32 v69, v77, s74, v155 bitop3:0xe4
	s_waitcnt lgkmcnt(2)
	v_mfma_f32_32x32x16_bf16 v[34:49], v[158:161], v[244:247], v[34:49]
	v_bfe_i32 v230, v194, 26, 1
	v_bfe_i32 v231, v194, 27, 1
	v_bitop3_b32 v70, v78, s74, v156 bitop3:0xe4
	v_max3_f32 v73, v71, v68, v69
	v_bitop3_b32 v71, v79, s74, v157 bitop3:0xe4
	v_bitop3_b32 v72, v80, s74, v230 bitop3:0xe4
	v_max3_f32 v76, v73, v70, v71
	v_bitop3_b32 v73, v81, s74, v231 bitop3:0xe4
	v_max3_f32 v76, v76, v72, v73
	v_mov_b32_e32 v77, v76
	s_waitcnt lgkmcnt(0)
	v_mfma_f32_32x32x16_bf16 v[18:33], v[158:161], v[248:251], v[18:33]
	s_cmp_eq_u64 s[36:37], 0
	s_cbranch_scc1 .Lp5_kw2_skip
	s_waitcnt vmcnt(0)
	ds_write_b128 v204, v[138:141] offset:49152
	ds_write_b128 v204, v[142:145] offset:57344
; __device__ __forceinline__ void partialSM(f32x16& p0, f32x16& p1, float& m_reg, float& mn, float& alpha) {
;     ...
;     { auto rr = __builtin_amdgcn_permlane32_swap(__float_as_uint(pmax), __float_as_uint(pmax), false, false);
;       pmax = fmaxf(__uint_as_float(rr[0]), __uint_as_float(rr[1])); }
;     constexpr float C2 = 1.4426950408889634f * SCALE;
;     if (__builtin_expect(__all((pmax - m_reg) * SCALE <= THR), 1)) { mn = m_reg; alpha = 1.f; }
;     else { mn = fmaxf(m_reg, pmax); alpha = __builtin_amdgcn_exp2f((m_reg - mn) * C2); m_reg = mn; }
;     const float mnL = -mn * C2;
; #pragma unroll
;     for (int r = 0; r < 16; ++r) p0[r] = fmaf(p0[r], C2, mnL);
; #pragma unroll
;     for (int r = 0; r < 16; ++r) p1[r] = fmaf(p1[r], C2, mnL);
; #pragma unroll
;     for (int r = 0; r < 16; ++r) p0[r] = __builtin_amdgcn_exp2f(p0[r]);
.Lp5_kw2_skip:
	s_nop 1
	v_permlane32_swap_b32_e32 v76, v77
	v_max_f32_e32 v76, v76, v77
	v_sub_f32_e32 v77, v76, v206
	v_mul_f32_e32 v77, 0x3db504f3, v77
	v_cmp_ge_f32_e32 vcc, s75, v77
	s_cmp_eq_u64 vcc, exec
	s_cselect_b64 s[6:7], -1, 0
	s_andn2_b64 vcc, exec, s[36:37]
	s_barrier
	s_cbranch_vccnz .LBB0_1307
	s_waitcnt vmcnt(0)
	ds_write_b128 v197, v[130:133] offset:16384
	ds_write_b128 v198, v[134:137] offset:16384
.LBB0_1307:
	v_max_f32_e32 v76, v206, v76
	v_sub_f32_e32 v77, v206, v76
	v_mul_f32_e32 v77, 0x3e0293ee, v77
	v_exp_f32_e32 v77, v77
	s_nop 0
	v_cndmask_b32_e64 v207, v77, 1.0, s[6:7]
	v_cmp_gt_f32_e32 vcc, 1.0, v207
	s_cbranch_vccz .LBB0_1311
	s_and_saveexec_b64 s[36:37], s[0:1]
	ds_write_b32 v185, v207 offset:128
	s_or_b64 exec, exec, s[36:37]
	s_waitcnt lgkmcnt(0)
	ds_read_b128 v[78:81], v183 offset:224
	ds_read_b128 v[130:133], v183 offset:192
	ds_read_b128 v[134:137], v183 offset:160
	ds_read_b128 v[138:141], v183 offset:128
	s_waitcnt lgkmcnt(3)
	v_pk_mul_f32 v[16:17], v[16:17], v[80:81]
	s_waitcnt lgkmcnt(2)
	v_pk_mul_f32 v[12:13], v[12:13], v[132:133]
	s_waitcnt lgkmcnt(1)
	v_pk_mul_f32 v[8:9], v[8:9], v[136:137]
	s_waitcnt lgkmcnt(0)
	v_pk_mul_f32 v[4:5], v[4:5], v[140:141]
	v_pk_mul_f32 v[14:15], v[14:15], v[78:79]
	v_pk_mul_f32 v[10:11], v[10:11], v[130:131]
	v_pk_mul_f32 v[6:7], v[6:7], v[134:135]
	v_pk_mul_f32 v[2:3], v[2:3], v[138:139]
	v_pk_mul_f32 v[64:65], v[64:65], v[80:81]
	v_pk_mul_f32 v[60:61], v[60:61], v[132:133]
	v_pk_mul_f32 v[56:57], v[56:57], v[136:137]
	v_pk_mul_f32 v[52:53], v[52:53], v[140:141]
	v_pk_mul_f32 v[62:63], v[62:63], v[78:79]
	v_pk_mul_f32 v[58:59], v[58:59], v[130:131]
	v_pk_mul_f32 v[54:55], v[54:55], v[134:135]
	v_pk_mul_f32 v[50:51], v[50:51], v[138:139]
	v_pk_mul_f32 v[48:49], v[48:49], v[80:81]
	v_pk_mul_f32 v[44:45], v[44:45], v[132:133]
	v_pk_mul_f32 v[40:41], v[40:41], v[136:137]
	v_pk_mul_f32 v[36:37], v[36:37], v[140:141]
	v_pk_mul_f32 v[46:47], v[46:47], v[78:79]
	v_pk_mul_f32 v[42:43], v[42:43], v[130:131]
	v_pk_mul_f32 v[38:39], v[38:39], v[134:135]
	v_pk_mul_f32 v[34:35], v[34:35], v[138:139]
	v_pk_mul_f32 v[32:33], v[32:33], v[80:81]
	v_pk_mul_f32 v[28:29], v[28:29], v[132:133]
	v_pk_mul_f32 v[24:25], v[24:25], v[136:137]
	v_pk_mul_f32 v[20:21], v[20:21], v[140:141]
	v_pk_mul_f32 v[30:31], v[30:31], v[78:79]
	v_pk_mul_f32 v[26:27], v[26:27], v[130:131]
	v_pk_mul_f32 v[22:23], v[22:23], v[134:135]
	v_pk_mul_f32 v[18:19], v[18:19], v[138:139]
.LBB0_1311:
	v_cndmask_b32_e64 v206, v76, v206, s[6:7]
	v_mul_f32_e32 v76, 0xbe0293ee, v206
	v_mov_b32_e32 v131, v76
	v_fmamk_f32 v77, v192, 0x3e0293ee, v76
	v_fmamk_f32 v78, v146, 0x3e0293ee, v76
	v_fmamk_f32 v79, v147, 0x3e0293ee, v76
	v_fmamk_f32 v80, v148, 0x3e0293ee, v76
	v_fmamk_f32 v81, v149, 0x3e0293ee, v76
	v_fmamk_f32 v130, v150, 0x3e0293ee, v76
	v_fmamk_f32 v88, v88, 0x3e0293ee, v76
	v_fmamk_f32 v89, v89, 0x3e0293ee, v76
	v_fmamk_f32 v90, v90, 0x3e0293ee, v76
	v_fmamk_f32 v91, v91, 0x3e0293ee, v76
	v_fmamk_f32 v92, v92, 0x3e0293ee, v76
	v_fmamk_f32 v93, v93, 0x3e0293ee, v76
	v_fmamk_f32 v94, v94, 0x3e0293ee, v76
	v_fmamk_f32 v95, v95, 0x3e0293ee, v76
	v_fmamk_f32 v96, v96, 0x3e0293ee, v76
	v_fmac_f32_e32 v131, 0x3e0293ee, v97
	v_exp_f32_e32 v219, v77
	v_exp_f32_e32 v220, v78
	v_exp_f32_e32 v221, v79
	v_exp_f32_e32 v222, v80
	v_exp_f32_e32 v223, v81
	v_exp_f32_e32 v225, v130
	v_exp_f32_e32 v224, v88
	v_exp_f32_e32 v226, v89
	v_exp_f32_e32 v211, v90
	v_exp_f32_e32 v212, v91
	v_exp_f32_e32 v213, v92
	v_exp_f32_e32 v215, v93
	v_exp_f32_e32 v214, v94
	v_exp_f32_e32 v216, v95
	v_exp_f32_e32 v217, v96
	v_exp_f32_e32 v218, v131
	v_pk_fma_f32 v[194:195], v[66:67], s[14:15], v[76:77] op_sel_hi:[1,0,0]
	v_fmac_f32_e32 v181, v177, v205
	v_pk_fma_f32 v[192:193], v[82:83], s[14:15], v[76:77] op_sel_hi:[1,0,0]
	v_pk_fma_f32 v[158:159], v[84:85], s[14:15], v[76:77] op_sel_hi:[1,0,0]
	v_pk_fma_f32 v[154:155], v[86:87], s[14:15], v[76:77] op_sel_hi:[1,0,0]
	v_pk_fma_f32 v[150:151], v[74:75], s[14:15], v[76:77] op_sel_hi:[1,0,0]
	v_pk_fma_f32 v[160:161], v[68:69], s[14:15], v[76:77] op_sel_hi:[1,0,0]
	v_pk_fma_f32 v[156:157], v[70:71], s[14:15], v[76:77] op_sel_hi:[1,0,0]
	v_pk_fma_f32 v[152:153], v[72:73], s[14:15], v[76:77] op_sel_hi:[1,0,0]
	v_fma_f32 v205, v181, v208, v209
	v_add_u32_e32 v179, 16, v179
	v_lshl_add_u64 v[188:189], v[188:189], 0, s[16:17]
	s_cmp_ge_u32 s82, s81
	v_lshl_add_u64 v[190:191], v[190:191], 0, s[16:17]
	s_waitcnt lgkmcnt(0)
	s_barrier
	s_cbranch_scc1 .LBB0_1313
	v_mov_b32_e32 v177, v207
	s_branch .LBB0_1299

; #define SBAR() __builtin_amdgcn_sched_barrier(0)
; #define SLOAD_H(Kp, Vp, k0) do { S.st_v0 = load8(ROW(Vp, k0, sr)); S.st_v1 = load8(ROW(Vp, k0, 32 + sr));              \
;                          S.st_k0 = load8(ROW(Kp, k0, sr)); S.st_k1 = load8(ROW(Kp, k0, 32 + sr)); } while (0)
; __device__ __forceinline__ void finishSM(f32x16& p0, f32x16& p1, float alpha, float& l_reg, bf16x8& pa0, bf16x8& pa1, bf16x8& pa2, bf16x8& pa3) {
; #pragma unroll
;     for (int r = 0; r < 16; ++r) p1[r] = __builtin_amdgcn_exp2f(p1[r]);
;     float ps = 0;
; #pragma unroll
;     for (int r = 0; r < 16; ++r) ps += p0[r];
; #pragma unroll
;     for (int r = 0; r < 16; ++r) ps += p1[r];
;     { auto rr = __builtin_amdgcn_permlane32_swap(__float_as_uint(ps), __float_as_uint(ps), false, false);
;       ps = __uint_as_float(rr[0]) + __uint_as_float(rr[1]); }
;     l_reg = l_reg * alpha + ps;
;     ...
;     PK4(p0, 0, pa0); PK4(p0, 8, pa1); PK4(p1, 0, pa2); PK4(p1, 8, pa3);
; __device__ __forceinline__ void attn_block(const BlockRef& cur, const BlockRef& nxt, char* lds, Seam& S) {
;     ...
;     mw = LDMASK(NT - 1);
;     SBAR(); qkt<1>(pB0, pB1, K_lds, r32, hi, S.qr); SBAR();
;     SLOAD_H(nxt.K, nxt.V, 0); SBAR();
; #pragma unroll
;     for (int d0 = 0; d0 < 8; ++d0) S.qr[d0] = load8(nxt.Q + (size_t)(wid * QBLK + r32) * LD + d0 * 16 + hi * 8);
;     SBAR();
;     finishSM(pA0, pA1, alA, l_reg, pa0, pa1, pa2, pa3); SBAR();
;     pv_tile<0>(o, vb0, pa0, pa1, pa2, pa3);
.LBB0_1313:
	v_mov_b32_e32 v66, v205
	s_nop 1
	v_permlane32_swap_b32_e32 v205, v66
	v_add_f32_e32 v205, v205, v66
	v_lshl_add_u32 v66, s81, 3, v165
	global_load_dwordx2 v[188:189], v66, s[68:69]
	ds_read_b128 v[66:69], v199 offset:49152
	ds_read_b128 v[82:85], v199 offset:49280
	ds_read_b128 v[86:89], v200 offset:49152
	ds_read_b128 v[90:93], v200 offset:49280
	s_waitcnt lgkmcnt(3)
	v_mfma_f32_32x32x16_bf16 v[66:81], v[66:69], v[126:129], 0
	s_waitcnt lgkmcnt(1)
	v_mfma_f32_32x32x16_bf16 v[66:81], v[86:89], v[122:125], v[66:81]
	ds_read_b128 v[86:89], v201 offset:49152
	ds_read_b128 v[94:97], v201 offset:49280
	s_waitcnt lgkmcnt(1)
	v_mfma_f32_32x32x16_bf16 v[66:81], v[86:89], v[118:121], v[66:81]
	ds_read_b128 v[86:89], v202 offset:49152
	ds_read_b128 v[130:133], v202 offset:49280
	s_waitcnt lgkmcnt(1)
	v_mfma_f32_32x32x16_bf16 v[66:81], v[86:89], v[114:117], v[66:81]
	v_mfma_f32_32x32x16_bf16 v[66:81], v[82:85], v[110:113], v[66:81]
	ds_read_b128 v[82:85], v199 offset:57344
	ds_read_b128 v[138:141], v199 offset:57472
	ds_read_b128 v[228:231], v200 offset:57344
	ds_read_b128 v[232:235], v200 offset:57472
	ds_read_b128 v[236:239], v201 offset:57344
	ds_read_b128 v[240:243], v201 offset:57472
	ds_read_b128 v[244:247], v202 offset:57344
	ds_read_b128 v[248:251], v202 offset:57472
	v_mfma_f32_32x32x16_bf16 v[66:81], v[90:93], v[106:109], v[66:81]
	v_mfma_f32_32x32x16_bf16 v[66:81], v[94:97], v[102:105], v[66:81]
	s_waitcnt lgkmcnt(8)
	v_mfma_f32_32x32x16_bf16 v[66:81], v[130:133], v[98:101], v[66:81]
	v_mov_b32_e32 v165, v167
	v_lshl_add_u64 v[86:87], s[62:63], 0, v[164:165]
	v_mov_b32_e32 v177, v167
	v_mov_b32_e32 v179, v167
	v_lshl_add_u64 v[86:87], v[86:87], 0, v[176:177]
	v_lshl_add_u64 v[88:89], s[62:63], 0, v[178:179]
	v_lshl_add_u64 v[88:89], v[88:89], 0, v[176:177]
	global_load_dwordx4 v[130:133], v[86:87], off
	global_load_dwordx4 v[134:137], v[88:89], off
	v_lshl_add_u64 v[86:87], s[60:61], 0, v[164:165]
	v_lshl_add_u64 v[86:87], v[86:87], 0, v[176:177]
	v_lshl_add_u64 v[88:89], s[60:61], 0, v[178:179]
	v_lshl_add_u64 v[88:89], v[88:89], 0, v[176:177]
	global_load_dwordx4 v[142:145], v[86:87], off
	global_load_dwordx4 v[146:149], v[88:89], off
	s_waitcnt lgkmcnt(7)
	v_mfma_f32_32x32x16_bf16 v[82:97], v[82:85], v[126:129], 0
	v_mov_b32_e32 v187, v167
	v_mov_b32_e32 v181, v167
	s_waitcnt lgkmcnt(5)
	v_mfma_f32_32x32x16_bf16 v[82:97], v[228:231], v[122:125], v[82:97]
	s_waitcnt lgkmcnt(3)
	v_mfma_f32_32x32x16_bf16 v[82:97], v[236:239], v[118:121], v[82:97]
	s_waitcnt lgkmcnt(1)
	v_mfma_f32_32x32x16_bf16 v[82:97], v[244:247], v[114:117], v[82:97]
	v_mfma_f32_32x32x16_bf16 v[82:97], v[138:141], v[110:113], v[82:97]
	v_lshlrev_b64 v[110:111], 11, v[186:187]
	v_lshl_add_u64 v[110:111], s[10:11], 0, v[110:111]
	v_lshl_add_u64 v[138:139], v[110:111], 0, v[180:181]
	v_mfma_f32_32x32x16_bf16 v[82:97], v[232:235], v[106:109], v[82:97]
	global_load_dwordx4 v[126:129], v[138:139], off
	global_load_dwordx4 v[122:125], v[138:139], off offset:32
	global_load_dwordx4 v[118:121], v[138:139], off offset:64
	global_load_dwordx4 v[114:117], v[138:139], off offset:96
	global_load_dwordx4 v[110:113], v[138:139], off offset:128
	global_load_dwordx4 v[106:109], v[138:139], off offset:160
	v_mfma_f32_32x32x16_bf16 v[82:97], v[240:243], v[102:105], v[82:97]
	global_load_dwordx4 v[102:105], v[138:139], off offset:192
	s_nop 0
	global_load_dwordx4 v[138:141], v[138:139], off offset:224
	s_waitcnt lgkmcnt(0)
	v_mfma_f32_32x32x16_bf16 v[82:97], v[248:251], v[98:101], v[82:97]
	v_add_f32_e32 v98, 0, v219
	v_add_f32_e32 v98, v220, v98
	v_add_f32_e32 v98, v221, v98
	v_add_f32_e32 v98, v222, v98
	v_add_f32_e32 v98, v223, v98
	v_add_f32_e32 v98, v225, v98
	v_add_f32_e32 v98, v224, v98
	v_add_f32_e32 v98, v226, v98
	v_add_f32_e32 v98, v211, v98
	v_add_f32_e32 v98, v212, v98
	v_add_f32_e32 v98, v213, v98
	v_add_f32_e32 v98, v215, v98
	v_exp_f32_e32 v100, v194
	v_add_f32_e32 v98, v214, v98
	v_exp_f32_e32 v101, v195
	v_add_f32_e32 v98, v216, v98
	v_exp_f32_e32 v165, v192
	v_add_f32_e32 v98, v217, v98
	v_exp_f32_e32 v172, v193
	v_add_f32_e32 v98, v218, v98
	v_exp_f32_e32 v173, v158
	v_add_f32_e32 v98, v100, v98
	v_exp_f32_e32 v174, v159
	v_add_f32_e32 v98, v101, v98
	v_exp_f32_e32 v175, v154
	v_add_f32_e32 v98, v165, v98
	v_exp_f32_e32 v177, v155
	v_add_f32_e32 v98, v172, v98
	v_exp_f32_e32 v179, v150
	v_add_f32_e32 v98, v173, v98
	v_exp_f32_e32 v181, v151
	v_add_f32_e32 v98, v174, v98
	v_exp_f32_e32 v186, v160
	v_add_f32_e32 v98, v175, v98
	v_exp_f32_e32 v187, v161
	v_add_f32_e32 v98, v177, v98
	v_exp_f32_e32 v192, v156
	v_add_f32_e32 v98, v179, v98
	v_exp_f32_e32 v193, v157
	v_add_f32_e32 v98, v181, v98
	v_exp_f32_e32 v194, v152
	v_add_f32_e32 v98, v186, v98
	v_exp_f32_e32 v195, v153
	v_add_f32_e32 v98, v187, v98
	v_add_f32_e32 v98, v192, v98
	v_add_f32_e32 v98, v193, v98
	v_add_f32_e32 v98, v194, v98
	v_add_f32_e32 v98, v98, v195
	v_mov_b32_e32 v99, v98
	v_cvt_pk_bf16_f32 v150, v219, v220
	v_cvt_pk_bf16_f32 v151, v221, v222
	v_cvt_pk_bf16_f32 v152, v223, v225
	v_cvt_pk_bf16_f32 v153, v224, v226
	v_permlane32_swap_b32_e32 v98, v99
	v_permlane32_swap_b32_e32 v150, v152
	v_permlane32_swap_b32_e32 v151, v153
	v_cvt_pk_bf16_f32 v154, v211, v212
	v_cvt_pk_bf16_f32 v155, v213, v215
	v_cvt_pk_bf16_f32 v156, v214, v216
	v_cvt_pk_bf16_f32 v157, v217, v218
	v_cvt_pk_bf16_f32 v158, v100, v101
	v_cvt_pk_bf16_f32 v159, v165, v172
	v_cvt_pk_bf16_f32 v160, v173, v174
	v_cvt_pk_bf16_f32 v161, v175, v177
	v_cvt_pk_bf16_f32 v190, v179, v181
	v_cvt_pk_bf16_f32 v191, v186, v187
	v_cvt_pk_bf16_f32 v192, v192, v193
	v_cvt_pk_bf16_f32 v193, v194, v195
	v_permlane32_swap_b32_e32 v154, v156
	v_permlane32_swap_b32_e32 v155, v157
	v_permlane32_swap_b32_e32 v158, v160
	v_permlane32_swap_b32_e32 v159, v161
	v_permlane32_swap_b32_e32 v190, v192
	v_permlane32_swap_b32_e32 v191, v193
	ds_read_b64_tr_b16 v[208:209], v1 offset:0
	ds_read_b64_tr_b16 v[210:211], v1 offset:0x800
	ds_read_b64_tr_b16 v[212:213], v1 offset:0x1000
	ds_read_b64_tr_b16 v[214:215], v1 offset:0x1800
	ds_read_b64_tr_b16 v[216:217], v1 offset:0x2000
	ds_read_b64_tr_b16 v[218:219], v1 offset:0x2800
	ds_read_b64_tr_b16 v[220:221], v1 offset:0x3000
	ds_read_b64_tr_b16 v[222:223], v1 offset:0x3800
	s_waitcnt lgkmcnt(0)
; __device__ __forceinline__ void sel_mask_tile(f32x16& p0, f32x16& p1, unsigned wlo, unsigned whi, int hi) {
;     const unsigned NEGB = 0xff800000u;
;     const unsigned lo = wlo >> (4 * hi), h2 = whi >> (4 * hi);
; #pragma unroll
;     for (int r = 0; r < 16; ++r) {
;         const int c = (r & 3) + 8 * (r >> 2);
;         const unsigned m0 = (unsigned)__builtin_amdgcn_sbfe((int)lo, c, 1), m1 = (unsigned)__builtin_amdgcn_sbfe((int)h2, c, 1);
;         p0[r] = __uint_as_float((__float_as_uint(p0[r]) & m0) | (NEGB & ~m0));
;         p1[r] = __uint_as_float((__float_as_uint(p1[r]) & m1) | (NEGB & ~m1));
;     }
; }
; __device__ __forceinline__ void partialSM(f32x16& p0, f32x16& p1, float& m_reg, float& mn, float& alpha) {
;     float pmax = p0[0];
; #pragma unroll
;     for (int r = 1; r < 16; ++r) pmax = fmaxf(pmax, p0[r]);
; #pragma unroll
;     for (int r = 0; r < 16; ++r) pmax = fmaxf(pmax, p1[r]);
;     { auto rr = __builtin_amdgcn_permlane32_swap(__float_as_uint(pmax), __float_as_uint(pmax), false, false);
;       pmax = fmaxf(__uint_as_float(rr[0]), __uint_as_float(rr[1])); }
;     constexpr float C2 = 1.4426950408889634f * SCALE;
;     if (__builtin_expect(__all((pmax - m_reg) * SCALE <= THR), 1)) { mn = m_reg; alpha = 1.f; }
;     else { mn = fmaxf(m_reg, pmax); alpha = __builtin_amdgcn_exp2f((m_reg - mn) * C2); m_reg = mn; }
; template <int VB>
; __device__ __forceinline__ void pv_tile(f32x16* o, int vb0, bf16x8 pa0, bf16x8 pa1, bf16x8 pa2, bf16x8 pa3) {
;     ...
;     PV_D0(0); PV_D0(1); PV_D0(2); PV_D0(3);
	s_nop 0
	v_mfma_f32_32x32x16_bf16 v[2:17], v[150:153], v[208:211], v[2:17]
	ds_read_b64_tr_b16 v[208:209], v1 offset:0x200
	ds_read_b64_tr_b16 v[210:211], v1 offset:0xa00
	v_mfma_f32_32x32x16_bf16 v[2:17], v[154:157], v[212:215], v[2:17]
	ds_read_b64_tr_b16 v[212:213], v1 offset:0x1200
	ds_read_b64_tr_b16 v[214:215], v1 offset:0x1a00
	v_mfma_f32_32x32x16_bf16 v[2:17], v[158:161], v[216:219], v[2:17]
	ds_read_b64_tr_b16 v[216:217], v1 offset:0x2200
	ds_read_b64_tr_b16 v[218:219], v1 offset:0x2a00
	ds_read_b64_tr_b16 v[224:225], v1 offset:0x3200
	ds_read_b64_tr_b16 v[226:227], v1 offset:0x3a00
	s_waitcnt lgkmcnt(0)
	v_mfma_f32_32x32x16_bf16 v[2:17], v[190:193], v[220:223], v[2:17]
	v_mfma_f32_32x32x16_bf16 v[50:65], v[150:153], v[208:211], v[50:65]
	ds_read_b64_tr_b16 v[208:209], v1 offset:0x400
	ds_read_b64_tr_b16 v[210:211], v1 offset:0xc00
	v_mfma_f32_32x32x16_bf16 v[50:65], v[154:157], v[212:215], v[50:65]
	ds_read_b64_tr_b16 v[212:213], v1 offset:0x1400
	ds_read_b64_tr_b16 v[214:215], v1 offset:0x1c00
	v_mfma_f32_32x32x16_bf16 v[50:65], v[158:161], v[216:219], v[50:65]
	ds_read_b64_tr_b16 v[216:217], v1 offset:0x2400
	ds_read_b64_tr_b16 v[218:219], v1 offset:0x2c00
	ds_read_b64_tr_b16 v[220:221], v1 offset:0x3400
	ds_read_b64_tr_b16 v[222:223], v1 offset:0x3c00
	s_waitcnt lgkmcnt(0)
	v_mfma_f32_32x32x16_bf16 v[50:65], v[190:193], v[224:227], v[50:65]
	v_mfma_f32_32x32x16_bf16 v[34:49], v[150:153], v[208:211], v[34:49]
	ds_read_b64_tr_b16 v[208:209], v1 offset:0x600
	ds_read_b64_tr_b16 v[210:211], v1 offset:0xe00
	v_mfma_f32_32x32x16_bf16 v[34:49], v[154:157], v[212:215], v[34:49]
	ds_read_b64_tr_b16 v[212:213], v1 offset:0x1600
	ds_read_b64_tr_b16 v[214:215], v1 offset:0x1e00
	v_mfma_f32_32x32x16_bf16 v[34:49], v[158:161], v[216:219], v[34:49]
	ds_read_b64_tr_b16 v[216:217], v1 offset:0x2600
	ds_read_b64_tr_b16 v[218:219], v1 offset:0x2e00
	ds_read_b64_tr_b16 v[224:225], v1 offset:0x3600
	ds_read_b64_tr_b16 v[226:227], v1 offset:0x3e00
	s_waitcnt lgkmcnt(0)
	v_mfma_f32_32x32x16_bf16 v[34:49], v[190:193], v[220:223], v[34:49]
	s_waitcnt vmcnt(12)
	v_lshrrev_b32_e32 v165, v163, v188
	v_lshrrev_b32_e32 v172, v163, v189
	v_bfe_i32 v100, v165, 0, 1
	v_bfe_i32 v101, v172, 0, 1
	v_bitop3_b32 v100, v66, s74, v100 bitop3:0xe4
	v_bfe_i32 v66, v165, 1, 1
	v_bitop3_b32 v82, v82, s74, v101 bitop3:0xe4
	v_mfma_f32_32x32x16_bf16 v[18:33], v[150:153], v[208:211], v[18:33]
	v_bfe_i32 v150, v172, 1, 1
	v_bitop3_b32 v101, v67, s74, v66 bitop3:0xe4
	v_bfe_i32 v66, v165, 2, 1
	v_bitop3_b32 v67, v83, s74, v150 bitop3:0xe4
	v_bfe_i32 v150, v172, 2, 1
	v_bitop3_b32 v83, v68, s74, v66 bitop3:0xe4
	v_bfe_i32 v66, v165, 3, 1
	v_bitop3_b32 v68, v84, s74, v150 bitop3:0xe4
	v_bfe_i32 v84, v172, 3, 1
	v_bitop3_b32 v150, v69, s74, v66 bitop3:0xe4
	v_bfe_i32 v66, v165, 8, 1
	v_bitop3_b32 v69, v85, s74, v84 bitop3:0xe4
	v_bfe_i32 v84, v172, 8, 1
	v_bitop3_b32 v151, v70, s74, v66 bitop3:0xe4
	v_bfe_i32 v66, v165, 9, 1
	v_bitop3_b32 v70, v86, s74, v84 bitop3:0xe4
	v_bfe_i32 v84, v172, 9, 1
	v_bitop3_b32 v152, v71, s74, v66 bitop3:0xe4
	v_bfe_i32 v66, v165, 10, 1
	v_bitop3_b32 v71, v87, s74, v84 bitop3:0xe4
	v_bfe_i32 v84, v172, 10, 1
	v_bitop3_b32 v87, v72, s74, v66 bitop3:0xe4
	v_bfe_i32 v66, v165, 11, 1
	v_bitop3_b32 v72, v88, s74, v84 bitop3:0xe4
	v_bfe_i32 v84, v172, 11, 1
	v_bitop3_b32 v88, v73, s74, v66 bitop3:0xe4
	v_bfe_i32 v66, v165, 16, 1
	v_bitop3_b32 v84, v89, s74, v84 bitop3:0xe4
	v_bfe_i32 v73, v172, 16, 1
	v_bitop3_b32 v89, v74, s74, v66 bitop3:0xe4
	v_bfe_i32 v66, v165, 17, 1
	v_bitop3_b32 v85, v90, s74, v73 bitop3:0xe4
	v_bfe_i32 v73, v172, 17, 1
	v_bitop3_b32 v90, v75, s74, v66 bitop3:0xe4
	v_bfe_i32 v66, v165, 18, 1
	v_bitop3_b32 v86, v91, s74, v73 bitop3:0xe4
	v_bfe_i32 v73, v172, 18, 1
	v_bitop3_b32 v91, v76, s74, v66 bitop3:0xe4
	v_bfe_i32 v66, v165, 19, 1
	v_bitop3_b32 v76, v92, s74, v73 bitop3:0xe4
	v_bfe_i32 v73, v172, 19, 1
	v_bitop3_b32 v92, v77, s74, v66 bitop3:0xe4
	v_bfe_i32 v66, v165, 24, 1
	v_bitop3_b32 v77, v93, s74, v73 bitop3:0xe4
	v_bitop3_b32 v93, v78, s74, v66 bitop3:0xe4
	v_bfe_i32 v66, v165, 25, 1
	v_bitop3_b32 v79, v79, s74, v66 bitop3:0xe4
	v_bfe_i32 v66, v165, 26, 1
	v_bfe_i32 v73, v172, 24, 1
	v_bitop3_b32 v80, v80, s74, v66 bitop3:0xe4
	v_bfe_i32 v66, v165, 27, 1
	v_bitop3_b32 v78, v94, s74, v73 bitop3:0xe4
	v_bitop3_b32 v81, v81, s74, v66 bitop3:0xe4
	v_max_f32_e32 v66, v101, v101
	v_max_f32_e32 v94, v100, v100
	v_max_f32_e32 v66, v94, v66
	v_max3_f32 v66, v66, v83, v150
	v_max3_f32 v66, v66, v151, v152
	v_max3_f32 v66, v66, v87, v88
	v_max3_f32 v66, v66, v89, v90
	v_max3_f32 v66, v66, v91, v92
	v_max3_f32 v66, v66, v93, v79
	v_mfma_f32_32x32x16_bf16 v[18:33], v[154:157], v[212:215], v[18:33]
	v_max3_f32 v66, v66, v80, v81
	v_max3_f32 v66, v66, v82, v67
	v_max3_f32 v66, v66, v68, v69
	v_max3_f32 v66, v66, v70, v71
	v_max3_f32 v66, v66, v72, v84
	v_bfe_i32 v73, v172, 25, 1
	v_max3_f32 v66, v66, v85, v86
	v_bitop3_b32 v73, v95, s74, v73 bitop3:0xe4
	v_bfe_i32 v74, v172, 26, 1
	v_bfe_i32 v75, v172, 27, 1
	v_max3_f32 v66, v66, v76, v77
	v_bitop3_b32 v74, v96, s74, v74 bitop3:0xe4
	v_bitop3_b32 v75, v97, s74, v75 bitop3:0xe4
	v_max3_f32 v66, v66, v78, v73
	v_mfma_f32_32x32x16_bf16 v[18:33], v[158:161], v[216:219], v[18:33]
	v_max3_f32 v66, v66, v74, v75
	v_mov_b32_e32 v94, v66
	s_nop 1
	v_permlane32_swap_b32_e32 v66, v94
	v_max_f32_e32 v94, v94, v94
	v_max_f32_e32 v66, v66, v66
	v_max_f32_e32 v66, v66, v94
	v_sub_f32_e32 v94, v66, v206
	v_mul_f32_e32 v95, 0x3db504f3, v94
	v_max_f32_e32 v94, v206, v206
	v_max_f32_e32 v94, v94, v66
	v_mfma_f32_32x32x16_bf16 v[18:33], v[190:193], v[224:227], v[18:33]
	v_sub_f32_e32 v66, v206, v94
	v_mul_f32_e32 v66, 0x3e0293ee, v66
	v_exp_f32_e32 v66, v66
	v_cmp_ge_f32_e32 vcc, s75, v95
	s_cmp_eq_u64 vcc, exec
	s_cselect_b64 s[6:7], -1, 0
	v_cndmask_b32_e64 v66, v66, 1.0, s[6:7]
	v_cmp_gt_f32_e32 vcc, 1.0, v66
	s_barrier
	s_cbranch_vccz .LBB0_1317
	s_and_saveexec_b64 s[36:37], s[0:1]
	ds_write_b32 v185, v66 offset:128
	s_or_b64 exec, exec, s[36:37]
	s_waitcnt lgkmcnt(0)
	ds_read_b128 v[154:157], v183 offset:224
	ds_read_b128 v[158:161], v183 offset:192
	ds_read_b128 v[172:175], v183 offset:160
	ds_read_b128 v[186:189], v183 offset:128
	s_waitcnt lgkmcnt(3)
	v_pk_mul_f32 v[16:17], v[16:17], v[156:157]
	s_waitcnt lgkmcnt(2)
	v_pk_mul_f32 v[12:13], v[12:13], v[160:161]
	s_waitcnt lgkmcnt(1)
	v_pk_mul_f32 v[8:9], v[8:9], v[174:175]
	s_waitcnt lgkmcnt(0)
	v_pk_mul_f32 v[4:5], v[4:5], v[188:189]
	v_pk_mul_f32 v[14:15], v[14:15], v[154:155]
	v_pk_mul_f32 v[10:11], v[10:11], v[158:159]
	v_pk_mul_f32 v[6:7], v[6:7], v[172:173]
	v_pk_mul_f32 v[2:3], v[2:3], v[186:187]
	v_pk_mul_f32 v[64:65], v[64:65], v[156:157]
	v_pk_mul_f32 v[60:61], v[60:61], v[160:161]
	v_pk_mul_f32 v[56:57], v[56:57], v[174:175]
	v_pk_mul_f32 v[52:53], v[52:53], v[188:189]
	v_pk_mul_f32 v[62:63], v[62:63], v[154:155]
	v_pk_mul_f32 v[58:59], v[58:59], v[158:159]
	v_pk_mul_f32 v[54:55], v[54:55], v[172:173]
	v_pk_mul_f32 v[50:51], v[50:51], v[186:187]
	v_pk_mul_f32 v[48:49], v[48:49], v[156:157]
	v_pk_mul_f32 v[44:45], v[44:45], v[160:161]
	v_pk_mul_f32 v[40:41], v[40:41], v[174:175]
	v_pk_mul_f32 v[36:37], v[36:37], v[188:189]
	v_pk_mul_f32 v[46:47], v[46:47], v[154:155]
	v_pk_mul_f32 v[42:43], v[42:43], v[158:159]
	v_pk_mul_f32 v[38:39], v[38:39], v[172:173]
	v_pk_mul_f32 v[34:35], v[34:35], v[186:187]
	v_pk_mul_f32 v[32:33], v[32:33], v[156:157]
	v_pk_mul_f32 v[28:29], v[28:29], v[160:161]
	v_pk_mul_f32 v[24:25], v[24:25], v[174:175]
	v_pk_mul_f32 v[20:21], v[20:21], v[188:189]
	v_pk_mul_f32 v[30:31], v[30:31], v[154:155]
	v_pk_mul_f32 v[26:27], v[26:27], v[158:159]
	v_pk_mul_f32 v[22:23], v[22:23], v[172:173]
	v_pk_mul_f32 v[18:19], v[18:19], v[186:187]
